# D attention loops: waves 4-7 start P.V right after the tile barrier and issue their K/V LDS-DMA pieces after P.V (while waves 0-3 are in their MFMA regions)
# speedup vs baseline: 1.0130x; 1.0056x over previous
; template <bool RSM> __device__ __forceinline__ void pv_d0(f32x16* o, f32x16& lacc, int vb, bf16x8 pa0, bf16x8 pa1, bf16x8 pa2, bf16x8 pa3) {
;     if (RSM) {
;         const bf16x8 ones = {0x3F80, 0x3F80, 0x3F80, 0x3F80, 0x3F80, 0x3F80, 0x3F80, 0x3F80};
;         lacc = __builtin_amdgcn_mfma_f32_32x32x16_bf16(pa0, ones, lacc, 0, 0, 0);
;         lacc = __builtin_amdgcn_mfma_f32_32x32x16_bf16(pa1, ones, lacc, 0, 0, 0);
;         lacc = __builtin_amdgcn_mfma_f32_32x32x16_bf16(pa2, ones, lacc, 0, 0, 0);
;         lacc = __builtin_amdgcn_mfma_f32_32x32x16_bf16(pa3, ones, lacc, 0, 0, 0); }
;     pv_one<0>(o[0], vb, pa0, pa1, pa2, pa3); pv_one<1>(o[1], vb, pa0, pa1, pa2, pa3); pv_one<2>(o[2], vb, pa0, pa1, pa2, pa3); pv_one<3>(o[3], vb, pa0, pa1, pa2, pa3);
; }
.Lmy_r2d_0:
	s_mov_b32 s38, s36
	s_mov_b32 s39, s36
	s_mov_b32 s37, s36
	v_mov_b64_e32 v[134:135], s[38:39]
	v_mov_b64_e32 v[132:133], s[36:37]
	s_lshl_b32 s23, s35, 14
	v_add_u32_e32 v0, s23, v230
	v_mfma_f32_32x32x16_bf16 v[96:111], v[6:9], v[132:135], v[96:111]
	ds_read_b64_tr_b16 v[136:137], v0 offset:0
	ds_read_b64_tr_b16 v[138:139], v0 offset:0x800
	ds_read_b64_tr_b16 v[140:141], v0 offset:0x1000
	ds_read_b64_tr_b16 v[142:143], v0 offset:0x1800
	ds_read_b64_tr_b16 v[192:193], v0 offset:0x2000
	ds_read_b64_tr_b16 v[194:195], v0 offset:0x2800
	ds_read_b64_tr_b16 v[196:197], v0 offset:0x3000
	v_mfma_f32_32x32x16_bf16 v[96:111], v[2:5], v[132:135], v[96:111]
	ds_read_b64_tr_b16 v[198:199], v0 offset:0x3800
	s_waitcnt lgkmcnt(0)
	v_mfma_f32_32x32x16_bf16 v[96:111], v[128:131], v[132:135], v[96:111]
	v_mfma_f32_32x32x16_bf16 v[96:111], v[10:13], v[132:135], v[96:111]
	v_mfma_f32_32x32x16_bf16 v[80:95], v[6:9], v[136:139], v[80:95]
	ds_read_b64_tr_b16 v[132:133], v0 offset:0x200
	ds_read_b64_tr_b16 v[134:135], v0 offset:0xa00
	ds_read_b64_tr_b16 v[136:137], v0 offset:0x1200
	ds_read_b64_tr_b16 v[138:139], v0 offset:0x1a00
	v_mfma_f32_32x32x16_bf16 v[80:95], v[2:5], v[140:143], v[80:95]
	ds_read_b64_tr_b16 v[140:141], v0 offset:0x2200
	ds_read_b64_tr_b16 v[142:143], v0 offset:0x2a00
	v_mfma_f32_32x32x16_bf16 v[80:95], v[128:131], v[192:195], v[80:95]
	ds_read_b64_tr_b16 v[192:193], v0 offset:0x3200
	ds_read_b64_tr_b16 v[194:195], v0 offset:0x3a00
	s_waitcnt lgkmcnt(0)
	v_mfma_f32_32x32x16_bf16 v[80:95], v[10:13], v[196:199], v[80:95]
	v_mfma_f32_32x32x16_bf16 v[64:79], v[6:9], v[132:135], v[64:79]
	ds_read_b64_tr_b16 v[132:133], v0 offset:0x400
	ds_read_b64_tr_b16 v[134:135], v0 offset:0xc00
	v_mfma_f32_32x32x16_bf16 v[64:79], v[2:5], v[136:139], v[64:79]
	ds_read_b64_tr_b16 v[136:137], v0 offset:0x1400
	ds_read_b64_tr_b16 v[138:139], v0 offset:0x1c00
	v_mfma_f32_32x32x16_bf16 v[64:79], v[128:131], v[140:143], v[64:79]
	ds_read_b64_tr_b16 v[140:141], v0 offset:0x2400
	ds_read_b64_tr_b16 v[142:143], v0 offset:0x2c00
	v_mfma_f32_32x32x16_bf16 v[64:79], v[10:13], v[192:195], v[64:79]
	ds_read_b64_tr_b16 v[192:193], v0 offset:0x3400
	ds_read_b64_tr_b16 v[194:195], v0 offset:0x3c00
	s_waitcnt lgkmcnt(0)
	v_mfma_f32_32x32x16_bf16 v[48:63], v[6:9], v[132:135], v[48:63]
	ds_read_b64_tr_b16 v[132:133], v0 offset:0x600
	ds_read_b64_tr_b16 v[134:135], v0 offset:0xe00
	v_mfma_f32_32x32x16_bf16 v[48:63], v[2:5], v[136:139], v[48:63]
	ds_read_b64_tr_b16 v[136:137], v0 offset:0x1600
	ds_read_b64_tr_b16 v[138:139], v0 offset:0x1e00
	v_mfma_f32_32x32x16_bf16 v[48:63], v[128:131], v[140:143], v[48:63]
	ds_read_b64_tr_b16 v[140:141], v0 offset:0x2600
	ds_read_b64_tr_b16 v[142:143], v0 offset:0x2e00
	v_mfma_f32_32x32x16_bf16 v[48:63], v[10:13], v[192:195], v[48:63]
	ds_read_b64_tr_b16 v[192:193], v0 offset:0x3600
	ds_read_b64_tr_b16 v[194:195], v0 offset:0x3e00
	s_waitcnt lgkmcnt(0)
	v_mfma_f32_32x32x16_bf16 v[32:47], v[6:9], v[132:135], v[32:47]
	s_and_b64 vcc, exec, s[0:1]
	v_mfma_f32_32x32x16_bf16 v[32:47], v[2:5], v[136:139], v[32:47]
	v_mfma_f32_32x32x16_bf16 v[32:47], v[128:131], v[140:143], v[32:47]
	v_mfma_f32_32x32x16_bf16 v[32:47], v[10:13], v[192:195], v[32:47]
	global_load_lds_dwordx4 v[214:215], off
	v_lshl_add_u64 v[214:215], v[214:215], 0, s[74:75]
	s_mov_b32 m0, s20
	s_nop 0
	global_load_lds_dwordx4 v[212:213], off
	v_lshl_add_u64 v[212:213], v[212:213], 0, s[74:75]
	s_add_i32 m0, s20, 0x2000
	s_nop 0
	global_load_lds_dwordx4 v[216:217], off
	v_lshl_add_u64 v[216:217], v[216:217], 0, s[74:75]
	s_cbranch_vccnz .LBB0_709
	s_branch .Lmy_r2ft_0
.Lmy_r2d_1:
	s_mov_b32 s38, s36
	s_mov_b32 s39, s36
	s_mov_b32 s37, s36
	v_mov_b64_e32 v[150:151], s[38:39]
	v_mov_b64_e32 v[148:149], s[36:37]
	s_lshl_b32 s37, s35, 14
	v_add_u32_e32 v14, s37, v230
	v_mfma_f32_32x32x16_bf16 v[96:111], v[6:9], v[148:151], v[96:111]
	ds_read_b64_tr_b16 v[152:153], v14 offset:0
	ds_read_b64_tr_b16 v[154:155], v14 offset:0x800
	ds_read_b64_tr_b16 v[156:157], v14 offset:0x1000
	ds_read_b64_tr_b16 v[158:159], v14 offset:0x1800
	ds_read_b64_tr_b16 v[192:193], v14 offset:0x2000
	ds_read_b64_tr_b16 v[194:195], v14 offset:0x2800
	ds_read_b64_tr_b16 v[196:197], v14 offset:0x3000
	v_mfma_f32_32x32x16_bf16 v[96:111], v[2:5], v[148:151], v[96:111]
	ds_read_b64_tr_b16 v[198:199], v14 offset:0x3800
	s_waitcnt lgkmcnt(0)
	v_mfma_f32_32x32x16_bf16 v[96:111], v[144:147], v[148:151], v[96:111]
	v_mfma_f32_32x32x16_bf16 v[96:111], v[10:13], v[148:151], v[96:111]
	v_mfma_f32_32x32x16_bf16 v[80:95], v[6:9], v[152:155], v[80:95]
	ds_read_b64_tr_b16 v[148:149], v14 offset:0x200
	ds_read_b64_tr_b16 v[150:151], v14 offset:0xa00
	ds_read_b64_tr_b16 v[152:153], v14 offset:0x1200
	ds_read_b64_tr_b16 v[154:155], v14 offset:0x1a00
	v_mfma_f32_32x32x16_bf16 v[80:95], v[2:5], v[156:159], v[80:95]
	ds_read_b64_tr_b16 v[156:157], v14 offset:0x2200
	ds_read_b64_tr_b16 v[158:159], v14 offset:0x2a00
	v_mfma_f32_32x32x16_bf16 v[80:95], v[144:147], v[192:195], v[80:95]
	ds_read_b64_tr_b16 v[192:193], v14 offset:0x3200
	ds_read_b64_tr_b16 v[194:195], v14 offset:0x3a00
	s_waitcnt lgkmcnt(0)
	v_mfma_f32_32x32x16_bf16 v[80:95], v[10:13], v[196:199], v[80:95]
	v_mfma_f32_32x32x16_bf16 v[64:79], v[6:9], v[148:151], v[64:79]
	ds_read_b64_tr_b16 v[148:149], v14 offset:0x400
	ds_read_b64_tr_b16 v[150:151], v14 offset:0xc00
	v_mfma_f32_32x32x16_bf16 v[64:79], v[2:5], v[152:155], v[64:79]
	ds_read_b64_tr_b16 v[152:153], v14 offset:0x1400
	ds_read_b64_tr_b16 v[154:155], v14 offset:0x1c00
	v_mfma_f32_32x32x16_bf16 v[64:79], v[144:147], v[156:159], v[64:79]
	ds_read_b64_tr_b16 v[156:157], v14 offset:0x2400
	ds_read_b64_tr_b16 v[158:159], v14 offset:0x2c00
	v_mfma_f32_32x32x16_bf16 v[64:79], v[10:13], v[192:195], v[64:79]
	ds_read_b64_tr_b16 v[192:193], v14 offset:0x3400
	ds_read_b64_tr_b16 v[194:195], v14 offset:0x3c00
	s_waitcnt lgkmcnt(0)
; template <bool RSM> __device__ __forceinline__ void pv_d0(f32x16* o, f32x16& lacc, int vb, bf16x8 pa0, bf16x8 pa1, bf16x8 pa2, bf16x8 pa3) {
;     if (RSM) {
;         const bf16x8 ones = {0x3F80, 0x3F80, 0x3F80, 0x3F80, 0x3F80, 0x3F80, 0x3F80, 0x3F80};
;         lacc = __builtin_amdgcn_mfma_f32_32x32x16_bf16(pa0, ones, lacc, 0, 0, 0);
;         lacc = __builtin_amdgcn_mfma_f32_32x32x16_bf16(pa1, ones, lacc, 0, 0, 0);
;         lacc = __builtin_amdgcn_mfma_f32_32x32x16_bf16(pa2, ones, lacc, 0, 0, 0);
;         lacc = __builtin_amdgcn_mfma_f32_32x32x16_bf16(pa3, ones, lacc, 0, 0, 0); }
;     pv_one<0>(o[0], vb, pa0, pa1, pa2, pa3); pv_one<1>(o[1], vb, pa0, pa1, pa2, pa3); pv_one<2>(o[2], vb, pa0, pa1, pa2, pa3); pv_one<3>(o[3], vb, pa0, pa1, pa2, pa3);
; }
	v_mfma_f32_32x32x16_bf16 v[48:63], v[6:9], v[148:151], v[48:63]
	ds_read_b64_tr_b16 v[148:149], v14 offset:0x600
	ds_read_b64_tr_b16 v[150:151], v14 offset:0xe00
	v_mfma_f32_32x32x16_bf16 v[48:63], v[2:5], v[152:155], v[48:63]
	ds_read_b64_tr_b16 v[152:153], v14 offset:0x1600
	ds_read_b64_tr_b16 v[154:155], v14 offset:0x1e00
	v_mfma_f32_32x32x16_bf16 v[48:63], v[144:147], v[156:159], v[48:63]
	ds_read_b64_tr_b16 v[156:157], v14 offset:0x2600
	ds_read_b64_tr_b16 v[158:159], v14 offset:0x2e00
	v_mfma_f32_32x32x16_bf16 v[48:63], v[10:13], v[192:195], v[48:63]
	ds_read_b64_tr_b16 v[192:193], v14 offset:0x3600
	ds_read_b64_tr_b16 v[194:195], v14 offset:0x3e00
	s_waitcnt lgkmcnt(0)
	v_mfma_f32_32x32x16_bf16 v[32:47], v[6:9], v[148:151], v[32:47]
	s_and_b64 vcc, exec, s[0:1]
	v_mfma_f32_32x32x16_bf16 v[32:47], v[2:5], v[152:155], v[32:47]
	v_mfma_f32_32x32x16_bf16 v[32:47], v[144:147], v[156:159], v[32:47]
	v_mfma_f32_32x32x16_bf16 v[32:47], v[10:13], v[192:195], v[32:47]
	global_load_lds_dwordx4 v[214:215], off
	v_lshl_add_u64 v[214:215], v[214:215], 0, s[74:75]
	s_mov_b32 m0, s22
	s_nop 0
	global_load_lds_dwordx4 v[212:213], off
	v_lshl_add_u64 v[212:213], v[212:213], 0, s[74:75]
	s_add_i32 m0, s22, 0x2000
	s_nop 0
	global_load_lds_dwordx4 v[216:217], off
	v_lshl_add_u64 v[216:217], v[216:217], 0, s[74:75]
	s_cbranch_vccnz .LBB0_724
	s_branch .Lmy_r2ft_1
.Lmy_r2d_2:
	s_mov_b32 s38, s36
	s_mov_b32 s39, s36
	s_mov_b32 s37, s36
	v_mov_b64_e32 v[118:119], s[38:39]
	v_mov_b64_e32 v[116:117], s[36:37]
	s_lshl_b32 s15, s18, 14
	v_add_u32_e32 v0, s15, v192
	v_mfma_f32_32x32x16_bf16 v[80:95], v[6:9], v[116:119], v[80:95]
	ds_read_b64_tr_b16 v[120:121], v0 offset:0
	ds_read_b64_tr_b16 v[122:123], v0 offset:0x800
	ds_read_b64_tr_b16 v[124:125], v0 offset:0x1000
	ds_read_b64_tr_b16 v[126:127], v0 offset:0x1800
	ds_read_b64_tr_b16 v[176:177], v0 offset:0x2000
	ds_read_b64_tr_b16 v[178:179], v0 offset:0x2800
	ds_read_b64_tr_b16 v[180:181], v0 offset:0x3000
	v_mfma_f32_32x32x16_bf16 v[80:95], v[2:5], v[116:119], v[80:95]
	ds_read_b64_tr_b16 v[182:183], v0 offset:0x3800
	s_waitcnt lgkmcnt(0)
	v_mfma_f32_32x32x16_bf16 v[80:95], v[112:115], v[116:119], v[80:95]
	v_mfma_f32_32x32x16_bf16 v[80:95], v[10:13], v[116:119], v[80:95]
	v_mfma_f32_32x32x16_bf16 v[64:79], v[6:9], v[120:123], v[64:79]
	ds_read_b64_tr_b16 v[116:117], v0 offset:0x200
	ds_read_b64_tr_b16 v[118:119], v0 offset:0xa00
	ds_read_b64_tr_b16 v[120:121], v0 offset:0x1200
	ds_read_b64_tr_b16 v[122:123], v0 offset:0x1a00
	v_mfma_f32_32x32x16_bf16 v[64:79], v[2:5], v[124:127], v[64:79]
	ds_read_b64_tr_b16 v[124:125], v0 offset:0x2200
	ds_read_b64_tr_b16 v[126:127], v0 offset:0x2a00
	v_mfma_f32_32x32x16_bf16 v[64:79], v[112:115], v[176:179], v[64:79]
	ds_read_b64_tr_b16 v[176:177], v0 offset:0x3200
	ds_read_b64_tr_b16 v[178:179], v0 offset:0x3a00
	s_waitcnt lgkmcnt(0)
	v_mfma_f32_32x32x16_bf16 v[64:79], v[10:13], v[180:183], v[64:79]
	v_mfma_f32_32x32x16_bf16 v[48:63], v[6:9], v[116:119], v[48:63]
	ds_read_b64_tr_b16 v[116:117], v0 offset:0x400
	ds_read_b64_tr_b16 v[118:119], v0 offset:0xc00
	v_mfma_f32_32x32x16_bf16 v[48:63], v[2:5], v[120:123], v[48:63]
	ds_read_b64_tr_b16 v[120:121], v0 offset:0x1400
	ds_read_b64_tr_b16 v[122:123], v0 offset:0x1c00
	v_mfma_f32_32x32x16_bf16 v[48:63], v[112:115], v[124:127], v[48:63]
	ds_read_b64_tr_b16 v[124:125], v0 offset:0x2400
	ds_read_b64_tr_b16 v[126:127], v0 offset:0x2c00
	v_mfma_f32_32x32x16_bf16 v[48:63], v[10:13], v[176:179], v[48:63]
	ds_read_b64_tr_b16 v[176:177], v0 offset:0x3400
	ds_read_b64_tr_b16 v[178:179], v0 offset:0x3c00
	s_waitcnt lgkmcnt(0)
	v_mfma_f32_32x32x16_bf16 v[32:47], v[6:9], v[116:119], v[32:47]
	ds_read_b64_tr_b16 v[116:117], v0 offset:0x600
	ds_read_b64_tr_b16 v[118:119], v0 offset:0xe00
	v_mfma_f32_32x32x16_bf16 v[32:47], v[2:5], v[120:123], v[32:47]
	ds_read_b64_tr_b16 v[120:121], v0 offset:0x1600
	ds_read_b64_tr_b16 v[122:123], v0 offset:0x1e00
	v_mfma_f32_32x32x16_bf16 v[32:47], v[112:115], v[124:127], v[32:47]
	ds_read_b64_tr_b16 v[124:125], v0 offset:0x2600
	ds_read_b64_tr_b16 v[126:127], v0 offset:0x2e00
	v_mfma_f32_32x32x16_bf16 v[32:47], v[10:13], v[176:179], v[32:47]
	ds_read_b64_tr_b16 v[176:177], v0 offset:0x3600
	ds_read_b64_tr_b16 v[178:179], v0 offset:0x3e00
	s_waitcnt lgkmcnt(0)
	v_mfma_f32_32x32x16_bf16 v[16:31], v[6:9], v[116:119], v[16:31]
	s_and_b64 vcc, exec, s[0:1]
	v_mfma_f32_32x32x16_bf16 v[16:31], v[2:5], v[120:123], v[16:31]
	v_mfma_f32_32x32x16_bf16 v[16:31], v[112:115], v[124:127], v[16:31]
	v_mfma_f32_32x32x16_bf16 v[16:31], v[10:13], v[176:179], v[16:31]
	global_load_lds_dwordx4 v[184:185], off
	v_lshl_add_u64 v[184:185], v[184:185], 0, s[74:75]
	s_mov_b32 m0, s12
	s_nop 0
	global_load_lds_dwordx4 v[186:187], off
	v_lshl_add_u64 v[186:187], v[186:187], 0, s[74:75]
	s_add_i32 m0, s12, 0x2000
	s_nop 0
	global_load_lds_dwordx4 v[188:189], off
	v_lshl_add_u64 v[188:189], v[188:189], 0, s[74:75]
	s_cbranch_vccnz .LBB0_784
	s_branch .Lmy_r2ft_2
; template <bool RSM> __device__ __forceinline__ void pv_d0(f32x16* o, f32x16& lacc, int vb, bf16x8 pa0, bf16x8 pa1, bf16x8 pa2, bf16x8 pa3) {
;     if (RSM) {
;         const bf16x8 ones = {0x3F80, 0x3F80, 0x3F80, 0x3F80, 0x3F80, 0x3F80, 0x3F80, 0x3F80};
;         lacc = __builtin_amdgcn_mfma_f32_32x32x16_bf16(pa0, ones, lacc, 0, 0, 0);
;         lacc = __builtin_amdgcn_mfma_f32_32x32x16_bf16(pa1, ones, lacc, 0, 0, 0);
;         lacc = __builtin_amdgcn_mfma_f32_32x32x16_bf16(pa2, ones, lacc, 0, 0, 0);
;         lacc = __builtin_amdgcn_mfma_f32_32x32x16_bf16(pa3, ones, lacc, 0, 0, 0); }
;     pv_one<0>(o[0], vb, pa0, pa1, pa2, pa3); pv_one<1>(o[1], vb, pa0, pa1, pa2, pa3); pv_one<2>(o[2], vb, pa0, pa1, pa2, pa3); pv_one<3>(o[3], vb, pa0, pa1, pa2, pa3);
; }
.Lmy_r2d_3:
	s_mov_b32 s38, s36
	s_mov_b32 s39, s36
	s_mov_b32 s37, s36
	v_mov_b64_e32 v[134:135], s[38:39]
	v_mov_b64_e32 v[132:133], s[36:37]
	s_lshl_b32 s31, s18, 14
	v_add_u32_e32 v14, s31, v192
	v_mfma_f32_32x32x16_bf16 v[80:95], v[6:9], v[132:135], v[80:95]
	ds_read_b64_tr_b16 v[136:137], v14 offset:0
	ds_read_b64_tr_b16 v[138:139], v14 offset:0x800
	ds_read_b64_tr_b16 v[140:141], v14 offset:0x1000
	ds_read_b64_tr_b16 v[142:143], v14 offset:0x1800
	ds_read_b64_tr_b16 v[176:177], v14 offset:0x2000
	ds_read_b64_tr_b16 v[178:179], v14 offset:0x2800
	ds_read_b64_tr_b16 v[180:181], v14 offset:0x3000
	v_mfma_f32_32x32x16_bf16 v[80:95], v[2:5], v[132:135], v[80:95]
	ds_read_b64_tr_b16 v[182:183], v14 offset:0x3800
	s_waitcnt lgkmcnt(0)
	v_mfma_f32_32x32x16_bf16 v[80:95], v[128:131], v[132:135], v[80:95]
	v_mfma_f32_32x32x16_bf16 v[80:95], v[10:13], v[132:135], v[80:95]
	v_mfma_f32_32x32x16_bf16 v[64:79], v[6:9], v[136:139], v[64:79]
	ds_read_b64_tr_b16 v[132:133], v14 offset:0x200
	ds_read_b64_tr_b16 v[134:135], v14 offset:0xa00
	ds_read_b64_tr_b16 v[136:137], v14 offset:0x1200
	ds_read_b64_tr_b16 v[138:139], v14 offset:0x1a00
	v_mfma_f32_32x32x16_bf16 v[64:79], v[2:5], v[140:143], v[64:79]
	ds_read_b64_tr_b16 v[140:141], v14 offset:0x2200
	ds_read_b64_tr_b16 v[142:143], v14 offset:0x2a00
	v_mfma_f32_32x32x16_bf16 v[64:79], v[128:131], v[176:179], v[64:79]
	ds_read_b64_tr_b16 v[176:177], v14 offset:0x3200
	ds_read_b64_tr_b16 v[178:179], v14 offset:0x3a00
	s_waitcnt lgkmcnt(0)
	v_mfma_f32_32x32x16_bf16 v[64:79], v[10:13], v[180:183], v[64:79]
	v_mfma_f32_32x32x16_bf16 v[48:63], v[6:9], v[132:135], v[48:63]
	ds_read_b64_tr_b16 v[132:133], v14 offset:0x400
	ds_read_b64_tr_b16 v[134:135], v14 offset:0xc00
	v_mfma_f32_32x32x16_bf16 v[48:63], v[2:5], v[136:139], v[48:63]
	ds_read_b64_tr_b16 v[136:137], v14 offset:0x1400
	ds_read_b64_tr_b16 v[138:139], v14 offset:0x1c00
	v_mfma_f32_32x32x16_bf16 v[48:63], v[128:131], v[140:143], v[48:63]
	ds_read_b64_tr_b16 v[140:141], v14 offset:0x2400
	ds_read_b64_tr_b16 v[142:143], v14 offset:0x2c00
	v_mfma_f32_32x32x16_bf16 v[48:63], v[10:13], v[176:179], v[48:63]
	ds_read_b64_tr_b16 v[176:177], v14 offset:0x3400
	ds_read_b64_tr_b16 v[178:179], v14 offset:0x3c00
	s_waitcnt lgkmcnt(0)
	v_mfma_f32_32x32x16_bf16 v[32:47], v[6:9], v[132:135], v[32:47]
	ds_read_b64_tr_b16 v[132:133], v14 offset:0x600
	ds_read_b64_tr_b16 v[134:135], v14 offset:0xe00
	v_mfma_f32_32x32x16_bf16 v[32:47], v[2:5], v[136:139], v[32:47]
	ds_read_b64_tr_b16 v[136:137], v14 offset:0x1600
	ds_read_b64_tr_b16 v[138:139], v14 offset:0x1e00
	v_mfma_f32_32x32x16_bf16 v[32:47], v[128:131], v[140:143], v[32:47]
	ds_read_b64_tr_b16 v[140:141], v14 offset:0x2600
	ds_read_b64_tr_b16 v[142:143], v14 offset:0x2e00
	v_mfma_f32_32x32x16_bf16 v[32:47], v[10:13], v[176:179], v[32:47]
	ds_read_b64_tr_b16 v[176:177], v14 offset:0x3600
	ds_read_b64_tr_b16 v[178:179], v14 offset:0x3e00
	s_waitcnt lgkmcnt(0)
	v_mfma_f32_32x32x16_bf16 v[16:31], v[6:9], v[132:135], v[16:31]
	s_and_b64 vcc, exec, s[0:1]
	v_mfma_f32_32x32x16_bf16 v[16:31], v[2:5], v[136:139], v[16:31]
	v_mfma_f32_32x32x16_bf16 v[16:31], v[128:131], v[140:143], v[16:31]
	v_mfma_f32_32x32x16_bf16 v[16:31], v[10:13], v[176:179], v[16:31]
	global_load_lds_dwordx4 v[184:185], off
	v_lshl_add_u64 v[184:185], v[184:185], 0, s[74:75]
	s_mov_b32 m0, s14
	s_nop 0
	global_load_lds_dwordx4 v[186:187], off
	v_lshl_add_u64 v[186:187], v[186:187], 0, s[74:75]
	s_add_i32 m0, s14, 0x2000
	s_nop 0
	global_load_lds_dwordx4 v[188:189], off
	v_lshl_add_u64 v[188:189], v[188:189], 0, s[74:75]
	s_cbranch_vccnz .LBB0_799
	s_branch .Lmy_r2ft_3
